# per-WG start skew in GEMM phases (1us/group bf16-epilogue, 3us/group residual-epilogue) to de-synchronize epilogue store bursts
# baseline (speedup 1.0000x reference)
.LBB0_22:
	s_add_i32 s8, s6, -1
	s_ashr_i32 s9, s8, 31
	s_lshr_b32 s9, s9, 29
	s_add_i32 s9, s8, s9
	s_ashr_i32 s12, s9, 3
	s_and_b32 s9, s9, -8
	s_sub_i32 s98, s8, s9
	s_mov_b32 s101, 0
	s_cmp_eq_u32 s98, 1
	s_cselect_b32 s101, 1, s101
	s_cmp_eq_u32 s98, 6
	s_cselect_b32 s101, 1, s101
	s_cmp_eq_u32 s98, 4
	s_cselect_b32 s101, 3, s101
	s_cmp_eq_u32 s98, 7
	s_cselect_b32 s101, 3, s101
	s_bfe_u32 s100, s94, 0x30003
	s_mul_i32 s100, s100, s101
	s_cmp_eq_u32 s100, 0
	s_cbranch_scc1 .Lskew_done
.Lskew_loop:
	s_sleep 32
	s_add_i32 s100, s100, -1
	s_cmp_lg_u32 s100, 0
	s_cbranch_scc1 .Lskew_loop
.Lskew_done:
	s_add_i32 s8, s6, -9
	s_cmp_lt_u32 s8, -15
	s_cselect_b64 s[10:11], -1, 0
	s_load_dwordx2 s[24:25], s[0:1], 0xa8
	v_writelane_b32 v255, s10, 0
	s_cmp_gt_u32 s8, -16
	s_nop 0
	v_writelane_b32 v255, s11, 1
	v_writelane_b32 v255, s8, 2
	s_cselect_b64 s[8:9], -1, 0
	s_load_dwordx2 s[10:11], s[0:1], 0xc8
	v_writelane_b32 v255, s8, 3
	s_nop 1
	v_writelane_b32 v255, s9, 4
	s_mul_i32 s9, s12, 0x6200000
	s_mul_hi_i32 s8, s12, 0x6200000
	s_waitcnt lgkmcnt(0)
	s_add_u32 s9, s24, s9
	v_writelane_b32 v255, s9, 5
	s_addc_u32 s8, s25, s8
	s_mul_i32 s9, s12, 0x6c000
	v_writelane_b32 v255, s8, 6
	s_mul_hi_i32 s8, s12, 0x6c000
	s_add_u32 s9, s10, s9
	v_writelane_b32 v255, s9, 7
	s_addc_u32 s8, s11, s8
	v_writelane_b32 v255, s8, 8
	s_cmp_lt_i32 s98, 4
	s_cbranch_scc1 .LBB0_34
	s_cmp_gt_i32 s98, 5
	s_mov_b64 s[8:9], -1
	s_cbranch_scc0 .LBB0_80
	s_cmp_lt_i32 s98, 7
	s_cbranch_scc1 .LBB0_65
	s_mov_b32 s76, s98
	s_cmp_eq_u32 s98, 7
	s_cbranch_scc0 .LBB0_64
	v_readlane_b32 s8, v255, 5
	s_add_u32 s13, s8, 0x4200000
	v_readlane_b32 s8, v255, 6
	s_addc_u32 s30, s8, 0
	v_readlane_b32 s8, v254, 2
	v_readlane_b32 s9, v254, 3
	s_load_dwordx2 s[10:11], s[0:1], 0xc0
	s_load_dword s58, s[8:9], 0x0
	s_mov_b32 s56, s94
	s_waitcnt vmcnt(7)
	v_mov_b32_e32 v18, v208
	s_cmpk_gt_i32 s56, 0x1ff
	v_readfirstlane_b32 s57, v18
	s_cbranch_scc1 .LBB0_50
	s_ashr_i32 s59, s56, 31
	s_lshr_b32 s8, s59, 29
	s_add_i32 s26, s56, s8
	s_and_b32 s8, s26, -8
	s_sub_i32 s25, s56, s8
	s_cmp_gt_i32 s25, -1
	s_mov_b64 s[8:9], -1
	s_cbranch_scc0 .LBB0_29
	s_lshl_b32 s24, s25, 6
	s_mov_b64 s[8:9], 0

	.amdhsa_kernel _Z4mega6Paramsii
		.amdhsa_group_segment_fixed_size 0
		.amdhsa_private_segment_fixed_size 0
		.amdhsa_kernarg_size 512
		.amdhsa_user_sgpr_count 2
		.amdhsa_user_sgpr_dispatch_ptr 0
		.amdhsa_user_sgpr_queue_ptr 0
		.amdhsa_user_sgpr_kernarg_segment_ptr 1
		.amdhsa_user_sgpr_dispatch_id 0
		.amdhsa_user_sgpr_kernarg_preload_length 0
		.amdhsa_user_sgpr_kernarg_preload_offset 0
		.amdhsa_user_sgpr_private_segment_size 0
		.amdhsa_uses_dynamic_stack 0
		.amdhsa_enable_private_segment 0
		.amdhsa_system_sgpr_workgroup_id_x 1
		.amdhsa_system_sgpr_workgroup_id_y 0
		.amdhsa_system_sgpr_workgroup_id_z 0
		.amdhsa_system_sgpr_workgroup_info 0
		.amdhsa_system_vgpr_workitem_id 2
		.amdhsa_next_free_vgpr 256
		.amdhsa_next_free_sgpr 102
		.amdhsa_accum_offset 256
		.amdhsa_reserve_vcc 1
		.amdhsa_float_round_mode_32 0
		.amdhsa_float_round_mode_16_64 0
		.amdhsa_float_denorm_mode_32 3
		.amdhsa_float_denorm_mode_16_64 3
		.amdhsa_dx10_clamp 1
		.amdhsa_ieee_mode 1
		.amdhsa_fp16_overflow 0
		.amdhsa_tg_split 0
		.amdhsa_exception_fp_ieee_invalid_op 0
		.amdhsa_exception_fp_denorm_src 0
		.amdhsa_exception_fp_ieee_div_zero 0
		.amdhsa_exception_fp_ieee_overflow 0
		.amdhsa_exception_fp_ieee_underflow 0
		.amdhsa_exception_fp_ieee_inexact 0
		.amdhsa_exception_int_div_zero 0
	.end_amdhsa_kernel

amdhsa.kernels:
  - .agpr_count:     0
    .args:
      - .offset:         0
        .size:           248
        .value_kind:     by_value
      - .offset:         248
        .size:           4
        .value_kind:     by_value
      - .offset:         252
        .size:           4
        .value_kind:     by_value
      - .offset:         256
        .size:           4
        .value_kind:     hidden_block_count_x
      - .offset:         260
        .size:           4
        .value_kind:     hidden_block_count_y
      - .offset:         264
        .size:           4
        .value_kind:     hidden_block_count_z
      - .offset:         268
        .size:           2
        .value_kind:     hidden_group_size_x
      - .offset:         270
        .size:           2
        .value_kind:     hidden_group_size_y
      - .offset:         272
        .size:           2
        .value_kind:     hidden_group_size_z
      - .offset:         274
        .size:           2
        .value_kind:     hidden_remainder_x
      - .offset:         276
        .size:           2
        .value_kind:     hidden_remainder_y
      - .offset:         278
        .size:           2
        .value_kind:     hidden_remainder_z
      - .offset:         296
        .size:           8
        .value_kind:     hidden_global_offset_x
      - .offset:         304
        .size:           8
        .value_kind:     hidden_global_offset_y
      - .offset:         312
        .size:           8
        .value_kind:     hidden_global_offset_z
      - .offset:         320
        .size:           2
        .value_kind:     hidden_grid_dims
      - .offset:         344
        .size:           8
        .value_kind:     hidden_multigrid_sync_arg
      - .offset:         376
        .size:           4
        .value_kind:     hidden_dynamic_lds_size
    .group_segment_fixed_size: 0
    .kernarg_segment_align: 8
    .kernarg_segment_size: 512
    .language:       OpenCL C
    .language_version:
      - 2
      - 0
    .max_flat_workgroup_size: 512
    .name:           _Z4mega6Paramsii
    .private_segment_fixed_size: 0
    .sgpr_count:     108
    .sgpr_spill_count: 76
    .symbol:         _Z4mega6Paramsii.kd
    .uniform_work_group_size: 1
    .uses_dynamic_stack: false
    .vgpr_count:     256
    .vgpr_spill_count: 0
    .wavefront_size: 64
